# v21: HGRN pass B: gate-chain row-major bf16 stores packed into two ds_write_b128; 8 lo/hi store pairs -> ds_write_b32 via row_ror:8 exchange
# baseline (speedup 1.0000x reference)
; __device__ __forceinline__ float bf2f(unsigned short v) { return __uint_as_float(((unsigned)v) << 16); }
; __device__ __forceinline__ float sigmoidf_(float x) { return __builtin_amdgcn_rcpf(1.0f + __expf(-x)); }
; template <bool PA>
; __device__ __forceinline__ void hgrn_scan(unsigned char* lds, const bf16* Q, const bf16* FFb, const bf16* FBb, const bf16* Ib, bf16* OFb, bf16* OBb, const float* lbp, float* segm, int slab, int tid) {
;     ...
;             float bl[16], kvv[16], qv[16]; float run = 1.f;
; #pragma unroll
;             for (int jj = 0; jj < 16; ++jj) { const float f = bf2f(fraw[jj]); const float fg = lb + (1.0f - lb) * sigmoidf_(f); run *= fg; bl[jj] = run; kvv[jj] = 1.0f - fg; qv[jj] = bf2f(qraw[jj]); }
;             tot[seg * 128 + c] = run;
;             { const size_t row = cbase + (dir ? 63 - jr : jr);
;               const u32x4_t w0 = *(const u32x4_t*)(Ib + row * 1024 + head * 128 + part * 16), w1 = *(const u32x4_t*)(Ib + row * 1024 + head * 128 + part * 16 + 8);
;               const unsigned wa[8] = {w0.x, w0.y, w0.z, w0.w, w1.x, w1.y, w1.z, w1.w};
; #pragma unroll
;               for (int q = 0; q < 8; ++q) { iT[(part * 16 + 2 * q) * 72 + jr] = (bf16)(wa[q] & 0xffff); iT[(part * 16 + 2 * q + 1) * 72 + jr] = (bf16)(wa[q] >> 16); } }
.LBB0_676:
	v_lshlrev_b32_e32 v34, 16, v182
	v_mul_f32_e32 v34, 0xbfb8aa3b, v34
	v_exp_f32_e32 v34, v34
	s_add_i32 s12, s24, 1
	s_and_b64 s[10:11], s[56:57], exec
	s_cselect_b32 s10, s65, s12
	v_add_f32_e32 v34, 1.0, v34
	v_rcp_f32_e32 v34, v34
	v_lshl_add_u32 v38, s10, 6, v213
	v_ashrrev_i32_e32 v39, 31, v38
	v_lshlrev_b64 v[230:231], 11, v[38:39]
	v_lshl_add_u64 v[230:231], v[82:83], 0, v[230:231]
	global_load_dwordx4 v[222:225], v[230:231], off
	global_load_dwordx4 v[226:229], v[230:231], off offset:16
	s_add_i32 s65, s65, 1
	v_fma_f32 v58, v211, v34, v210
	v_lshlrev_b32_e32 v34, 16, v184
	v_mul_f32_e32 v34, 0xbfb8aa3b, v34
	v_exp_f32_e32 v34, v34
	s_cmp_ge_i32 s65, s67
	s_cselect_b64 s[10:11], -1, 0
	s_and_b64 vcc, exec, s[10:11]
	v_add_f32_e32 v34, 1.0, v34
	v_rcp_f32_e32 v34, v34
	s_nop 0
	v_fma_f32 v239, v211, v34, v210
	v_lshlrev_b32_e32 v34, 16, v185
	v_mul_f32_e32 v34, 0xbfb8aa3b, v34
	v_exp_f32_e32 v34, v34
	v_mul_f32_e32 v64, v58, v239
	v_add_f32_e32 v34, 1.0, v34
	v_rcp_f32_e32 v34, v34
	s_nop 0
	v_fma_f32 v240, v211, v34, v210
	v_lshlrev_b32_e32 v34, 16, v186
	v_mul_f32_e32 v34, 0xbfb8aa3b, v34
	v_exp_f32_e32 v34, v34
	v_mul_f32_e32 v62, v64, v240
	v_add_f32_e32 v34, 1.0, v34
	v_rcp_f32_e32 v34, v34
	s_nop 0
	v_fma_f32 v241, v211, v34, v210
	v_lshlrev_b32_e32 v34, 16, v193
	v_mul_f32_e32 v34, 0xbfb8aa3b, v34
	v_exp_f32_e32 v34, v34
	v_mul_f32_e32 v234, v62, v241
	v_add_f32_e32 v34, 1.0, v34
	v_rcp_f32_e32 v34, v34
	s_nop 0
	v_fma_f32 v242, v211, v34, v210
	v_lshlrev_b32_e32 v34, 16, v195
	v_mul_f32_e32 v34, 0xbfb8aa3b, v34
	v_exp_f32_e32 v34, v34
	v_mul_f32_e32 v237, v234, v242
	v_add_f32_e32 v34, 1.0, v34
	v_rcp_f32_e32 v34, v34
	s_nop 0
	v_fma_f32 v243, v211, v34, v210
	v_lshlrev_b32_e32 v34, 16, v205
	v_mul_f32_e32 v34, 0xbfb8aa3b, v34
	v_exp_f32_e32 v34, v34
	v_mul_f32_e32 v238, v237, v243
	v_add_f32_e32 v34, 1.0, v34
	v_rcp_f32_e32 v34, v34
	s_nop 0
	v_fma_f32 v244, v211, v34, v210
	v_lshlrev_b32_e32 v34, 16, v206
	v_mul_f32_e32 v34, 0xbfb8aa3b, v34
	v_exp_f32_e32 v34, v34
	v_mul_f32_e32 v236, v238, v244
	v_add_f32_e32 v34, 1.0, v34
	v_rcp_f32_e32 v34, v34
	s_nop 0
	v_fma_f32 v245, v211, v34, v210
	v_lshlrev_b32_e32 v34, 16, v207
	v_mul_f32_e32 v34, 0xbfb8aa3b, v34
	v_exp_f32_e32 v34, v34
	v_mul_f32_e32 v235, v236, v245
	v_add_f32_e32 v34, 1.0, v34
	v_rcp_f32_e32 v34, v34
	s_nop 0
	v_fma_f32 v246, v211, v34, v210
	v_lshlrev_b32_e32 v34, 16, v208
	v_mul_f32_e32 v34, 0xbfb8aa3b, v34
	v_exp_f32_e32 v34, v34
	v_mul_f32_e32 v233, v235, v246
	v_add_f32_e32 v34, 1.0, v34
	v_rcp_f32_e32 v34, v34
	s_nop 0
	v_fma_f32 v247, v211, v34, v210
	v_lshlrev_b32_e32 v34, 16, v209
	v_mul_f32_e32 v34, 0xbfb8aa3b, v34
	v_exp_f32_e32 v34, v34
	v_mul_f32_e32 v65, v233, v247
	v_add_f32_e32 v34, 1.0, v34
	v_rcp_f32_e32 v34, v34
	s_nop 0
	v_fma_f32 v248, v211, v34, v210
	v_lshlrev_b32_e32 v34, 16, v212
	v_mul_f32_e32 v34, 0xbfb8aa3b, v34
	v_exp_f32_e32 v34, v34
	v_mul_f32_e32 v63, v65, v248
	v_add_f32_e32 v34, 1.0, v34
	v_rcp_f32_e32 v34, v34
	s_nop 0
	v_fma_f32 v249, v211, v34, v210
	v_lshlrev_b32_e32 v34, 16, v214
	v_mul_f32_e32 v34, 0xbfb8aa3b, v34
	v_exp_f32_e32 v34, v34
	v_mul_f32_e32 v61, v63, v249
	v_add_f32_e32 v34, 1.0, v34
	v_rcp_f32_e32 v34, v34
	s_nop 0
	v_fma_f32 v250, v211, v34, v210
	v_lshlrev_b32_e32 v34, 16, v217
	v_mul_f32_e32 v34, 0xbfb8aa3b, v34
	v_exp_f32_e32 v34, v34
	v_mul_f32_e32 v60, v61, v250
	v_add_f32_e32 v34, 1.0, v34
	v_rcp_f32_e32 v34, v34
	s_nop 0
	v_fma_f32 v251, v211, v34, v210
	v_lshlrev_b32_e32 v34, 16, v219
	v_mul_f32_e32 v34, 0xbfb8aa3b, v34
	v_exp_f32_e32 v34, v34
	v_mul_f32_e32 v59, v60, v251
	v_add_f32_e32 v34, 1.0, v34
	v_rcp_f32_e32 v34, v34
	s_nop 0
	v_fma_f32 v252, v211, v34, v210
	s_waitcnt vmcnt(2)
	v_lshlrev_b32_e32 v34, 16, v220
	v_mul_f32_e32 v34, 0xbfb8aa3b, v34
	v_exp_f32_e32 v34, v34
	v_mul_f32_e32 v57, v59, v252
	v_add_f32_e32 v34, 1.0, v34
	v_rcp_f32_e32 v34, v34
	s_nop 0
	v_fma_f32 v146, v211, v34, v210
	v_mul_f32_e32 v56, v57, v146
	ds_write_b32 v90, v56
	s_waitcnt vmcnt(1)
	v_bfe_u32 v139, v203, 3, 1
	v_sub_u32_e32 v138, 0, v139
	v_and_b32_e32 v138, 0x6060606, v138
	v_xor_b32_e32 v144, 0x5040100, v138
	v_mul_u32_u24_e32 v139, 0x8e, v139
	s_nop 1
	v_mov_b32_dpp v138, v222 row_ror:8 row_mask:0xf bank_mask:0xf
	v_add_u32_e32 v145, v139, v129
	v_perm_b32 v138, v138, v222, v144
	ds_write_b32 v145, v138 offset:62464
	s_nop 1
	v_mov_b32_dpp v138, v223 row_ror:8 row_mask:0xf bank_mask:0xf
	v_perm_b32 v138, v138, v223, v144
	ds_write_b32 v145, v138 offset:62752
	s_nop 1
	v_mov_b32_dpp v138, v224 row_ror:8 row_mask:0xf bank_mask:0xf
	v_add_u32_e32 v145, v139, v134
	v_perm_b32 v138, v138, v224, v144
	ds_write_b32 v145, v138 offset:63040
	s_nop 1
	v_mov_b32_dpp v138, v225 row_ror:8 row_mask:0xf bank_mask:0xf
	v_perm_b32 v138, v138, v225, v144
	ds_write_b32 v145, v138 offset:63328
	s_waitcnt vmcnt(0)
	s_nop 1
	v_mov_b32_dpp v138, v226 row_ror:8 row_mask:0xf bank_mask:0xf
	v_perm_b32 v138, v138, v226, v144
	ds_write_b32 v145, v138 offset:63616
	s_nop 1
	v_mov_b32_dpp v138, v227 row_ror:8 row_mask:0xf bank_mask:0xf
	v_perm_b32 v138, v138, v227, v144
	ds_write_b32 v145, v138 offset:63904
	s_nop 1
	v_mov_b32_dpp v138, v228 row_ror:8 row_mask:0xf bank_mask:0xf
	v_add_u32_e32 v145, v139, v129
	v_perm_b32 v138, v138, v228, v144
	ds_write_b32 v145, v138 offset:64192
	s_nop 1
	v_mov_b32_dpp v138, v229 row_ror:8 row_mask:0xf bank_mask:0xf
	v_perm_b32 v138, v138, v229, v144
	ds_write_b32 v145, v138 offset:64480
	s_cbranch_vccnz .LBB0_678
; template <bool PA>
; __device__ __forceinline__ void hgrn_scan(unsigned char* lds, const bf16* Q, const bf16* FFb, const bf16* FBb, const bf16* Ib, bf16* OFb, bf16* OBb, const float* lbp, float* segm, int slab, int tid) {
;     ...
;             if (p + 1 < p1) { const int nb = seqbase + (dir ? nch - 2 - p : p + 1) * 64;
; #pragma unroll
;                 for (int jj = 0; jj < 16; ++jj) { const int j = 16 * seg + jj; const unsigned bo = ((unsigned)(nb + (dir ? 63 - j : j)) * 1024u + (unsigned)hc) * 2u; qraw[jj] = PA ? (unsigned short)0 : *(const unsigned short*)((const char*)Q + bo); fraw[jj] = *(const unsigned short*)((const char*)Fp + bo); } }
	s_and_b64 s[12:13], s[56:57], exec
	s_cselect_b32 s12, s65, s24
	s_lshl_b32 s12, s12, 6
	s_add_i32 s12, s12, s66
	v_add_u32_e32 v34, s12, v0
	v_lshl_or_b32 v34, v34, 11, v175
	v_add_u32_e32 v35, s12, v176
	v_add_u32_e32 v36, s12, v177
	v_add_u32_e32 v37, s12, v178
	v_lshl_or_b32 v35, v35, 11, v175
	v_lshl_or_b32 v36, v36, 11, v175
	v_lshl_or_b32 v37, v37, 11, v175
	global_load_ushort v81, v34, s[16:17]
	global_load_ushort v182, v34, s[8:9]
	global_load_ushort v215, v35, s[16:17]
	global_load_ushort v184, v35, s[8:9]
	global_load_ushort v216, v36, s[16:17]
	global_load_ushort v185, v36, s[8:9]
	global_load_ushort v218, v37, s[16:17]
	global_load_ushort v186, v37, s[8:9]
	v_add_u32_e32 v34, s12, v179
	v_lshl_or_b32 v34, v34, 11, v175
	v_add_u32_e32 v35, s12, v180
	v_add_u32_e32 v36, s12, v181
	v_add_u32_e32 v37, s12, v183
	v_lshl_or_b32 v35, v35, 11, v175
	v_lshl_or_b32 v36, v36, 11, v175
	v_lshl_or_b32 v37, v37, 11, v175
	global_load_ushort v221, v34, s[16:17]
	global_load_ushort v193, v34, s[8:9]
	global_load_ushort v222, v35, s[16:17]
	global_load_ushort v195, v35, s[8:9]
	global_load_ushort v223, v36, s[16:17]
	global_load_ushort v205, v36, s[8:9]
	global_load_ushort v224, v37, s[16:17]
	global_load_ushort v206, v37, s[8:9]
	v_add_u32_e32 v34, s12, v187
	v_lshl_or_b32 v34, v34, 11, v175
	v_add_u32_e32 v35, s12, v188
	v_add_u32_e32 v36, s12, v189
	v_add_u32_e32 v37, s12, v190
	v_lshl_or_b32 v35, v35, 11, v175
	v_lshl_or_b32 v36, v36, 11, v175
	v_lshl_or_b32 v37, v37, 11, v175
	global_load_ushort v225, v34, s[16:17]
	global_load_ushort v207, v34, s[8:9]
	global_load_ushort v226, v35, s[16:17]
	global_load_ushort v208, v35, s[8:9]
	global_load_ushort v227, v36, s[16:17]
	global_load_ushort v209, v36, s[8:9]
	global_load_ushort v228, v37, s[16:17]
	global_load_ushort v212, v37, s[8:9]
	v_add_u32_e32 v34, s12, v191
	v_lshl_or_b32 v34, v34, 11, v175
	v_add_u32_e32 v35, s12, v192
	v_add_u32_e32 v36, s12, v194
	v_add_u32_e32 v37, s12, v204
	v_lshl_or_b32 v35, v35, 11, v175
	v_lshl_or_b32 v36, v36, 11, v175
	v_lshl_or_b32 v37, v37, 11, v175
	global_load_ushort v229, v34, s[16:17]
	global_load_ushort v214, v34, s[8:9]
	global_load_ushort v230, v35, s[16:17]
	global_load_ushort v217, v35, s[8:9]
	global_load_ushort v231, v36, s[16:17]
	global_load_ushort v219, v36, s[8:9]
	global_load_ushort v232, v37, s[16:17]
	global_load_ushort v220, v37, s[8:9]

; __device__ __forceinline__ unsigned f2bf(float f) { return pk2(f, 0.f) & 0xffffu; }
; template <bool PA>
; __device__ __forceinline__ void hgrn_scan(unsigned char* lds, const bf16* Q, const bf16* FFb, const bf16* FBb, const bf16* Ib, bf16* OFb, bf16* OBb, const float* lbp, float* segm, int slab, int tid) {
;     ...
;             const float t0 = tot[c], t1 = tot[128 + c], t2 = tot[256 + c], t3 = tot[384 + c];
;             const float off = seg == 0 ? 1.f : (seg == 1 ? t0 : (seg == 2 ? t0 * t1 : t0 * t1 * t2));
;             const float aref = t0 * t1, alast = (t0 * t1) * (t2 * t3); const float iaref = __builtin_amdgcn_rcpf(aref);
; #pragma unroll
;             for (int jj = 0; jj < 16; ++jj) { const int j = 16 * seg + jj; const float at = off * bl[jj];
;                 const float ke = kvv[jj] * (aref * __builtin_amdgcn_rcpf(at)); const bf16 kb = (bf16)f2bf(ke); kinT[c * 72 + j] = kb;
;                 if (!PA) { const float qe = qv[jj] * (at * iaref); qin[j * 136 + c] = (bf16)f2bf(qe); kin[j * 136 + c] = kb; } }
;             if (seg == 0) { c1[c] = aref; c2[c] = alast * iaref; gtv[c] = alast; gprod *= alast; }
.LBB0_686:
	s_or_b64 exec, exec, s[12:13]
	s_waitcnt lgkmcnt(1)
	v_mul_f32_e32 v36, v36, v37
	v_rcp_f32_e32 v37, v36
	v_lshlrev_b64 v[86:87], 10, v[38:39]
	v_sub_f32_e32 v38, 1.0, v58
	v_mul_f32_e32 v58, v58, v147
	v_sub_f32_e32 v201, 1.0, v241
	v_sub_f32_e32 v241, 1.0, v244
	v_sub_f32_e32 v244, 1.0, v247
	v_sub_f32_e32 v247, 1.0, v250
	v_rcp_f32_e32 v250, v58
	v_lshlrev_b32_e32 v39, 16, v40
	v_mul_f32_e32 v58, v37, v58
	v_mul_f32_e32 v39, v58, v39
	v_mul_f32_e32 v58, v64, v147
	v_rcp_f32_e32 v64, v58
	v_mul_f32_e32 v250, v36, v250
	v_mul_f32_e32 v38, v38, v250
	v_cvt_pk_bf16_f32 v38, v38, s0
	v_cvt_pk_bf16_f32 v39, v39, s0
	v_sub_f32_e32 v40, 1.0, v239
	v_and_b32_e32 v138, 0xffff, v38
	ds_write_b16 v132, v39
	ds_write_b16 v132, v38 offset:17408
	v_mul_f32_e32 v38, v36, v64
	v_lshlrev_b32_e32 v41, 16, v41
	v_mul_f32_e32 v38, v40, v38
	v_mul_f32_e32 v39, v37, v58
	v_mul_f32_e32 v40, v62, v147
	v_mul_f32_e32 v39, v39, v41
	v_rcp_f32_e32 v41, v40
	v_cvt_pk_bf16_f32 v38, v38, s0
	v_cvt_pk_bf16_f32 v39, v39, s0
	v_lshl_or_b32 v140, v38, 16, v138
	ds_write_b16 v132, v39 offset:272
	ds_write_b16 v132, v38 offset:17680
	v_mul_f32_e32 v39, v37, v40
	v_mul_f32_e32 v40, v234, v147
	v_sub_f32_e32 v200, 1.0, v240
	v_lshlrev_b32_e32 v42, 16, v42
	v_mul_f32_e32 v38, v36, v41
	v_rcp_f32_e32 v41, v40
	v_mul_f32_e32 v38, v200, v38
	v_mul_f32_e32 v39, v39, v42
	v_cvt_pk_bf16_f32 v38, v38, s0
	v_cvt_pk_bf16_f32 v39, v39, s0
	v_and_b32_e32 v138, 0xffff, v38
	ds_write_b16 v132, v39 offset:544
	ds_write_b16 v132, v38 offset:17952
	v_mul_f32_e32 v39, v37, v40
	v_mul_f32_e32 v40, v237, v147
	v_lshlrev_b32_e32 v43, 16, v43
	v_mul_f32_e32 v38, v36, v41
	v_rcp_f32_e32 v41, v40
	v_mul_f32_e32 v38, v201, v38
	v_mul_f32_e32 v39, v39, v43
	v_cvt_pk_bf16_f32 v38, v38, s0
	v_cvt_pk_bf16_f32 v39, v39, s0
	v_lshl_or_b32 v141, v38, 16, v138
	ds_write_b16 v132, v39 offset:816
	ds_write_b16 v132, v38 offset:18224
	v_mul_f32_e32 v39, v37, v40
	v_mul_f32_e32 v40, v238, v147
	v_sub_f32_e32 v239, 1.0, v242
	v_lshlrev_b32_e32 v44, 16, v44
	v_mul_f32_e32 v38, v36, v41
	v_rcp_f32_e32 v41, v40
	v_mul_f32_e32 v38, v239, v38
	v_mul_f32_e32 v39, v39, v44
	v_cvt_pk_bf16_f32 v38, v38, s0
	v_cvt_pk_bf16_f32 v39, v39, s0
	v_and_b32_e32 v138, 0xffff, v38
	ds_write_b16 v137, v39 offset:1088
	ds_write_b16 v137, v38 offset:18496
	v_mul_f32_e32 v39, v37, v40
	v_mul_f32_e32 v40, v236, v147
	v_sub_f32_e32 v240, 1.0, v243
	v_lshlrev_b32_e32 v45, 16, v45
	v_mul_f32_e32 v38, v36, v41
	v_rcp_f32_e32 v41, v40
	v_mul_f32_e32 v38, v240, v38
	v_mul_f32_e32 v39, v39, v45
	v_cvt_pk_bf16_f32 v38, v38, s0
	v_cvt_pk_bf16_f32 v39, v39, s0
	v_lshl_or_b32 v142, v38, 16, v138
	ds_write_b16 v137, v39 offset:1360
	ds_write_b16 v137, v38 offset:18768
	v_mul_f32_e32 v39, v37, v40
	v_mul_f32_e32 v40, v235, v147
	v_lshlrev_b32_e32 v46, 16, v46
	v_mul_f32_e32 v38, v36, v41
	v_rcp_f32_e32 v41, v40
	v_mul_f32_e32 v38, v241, v38
	v_mul_f32_e32 v39, v39, v46
	v_cvt_pk_bf16_f32 v38, v38, s0
	v_cvt_pk_bf16_f32 v39, v39, s0
	v_and_b32_e32 v138, 0xffff, v38
	ds_write_b16 v137, v39 offset:1632
	ds_write_b16 v137, v38 offset:19040
	v_mul_f32_e32 v39, v37, v40
	v_mul_f32_e32 v40, v233, v147
	v_sub_f32_e32 v242, 1.0, v245
	v_lshlrev_b32_e32 v47, 16, v47
	v_mul_f32_e32 v38, v36, v41
	v_rcp_f32_e32 v41, v40
	v_mul_f32_e32 v38, v242, v38
	v_mul_f32_e32 v39, v39, v47
	v_cvt_pk_bf16_f32 v38, v38, s0
	v_cvt_pk_bf16_f32 v39, v39, s0
	v_lshl_or_b32 v143, v38, 16, v138
	ds_write_b128 v131, v[140:143] offset:34816
	ds_write_b16 v137, v39 offset:1904
	ds_write_b16 v137, v38 offset:19312
	v_mul_f32_e32 v39, v37, v40
	v_mul_f32_e32 v40, v65, v147
	v_sub_f32_e32 v243, 1.0, v246
	v_lshlrev_b32_e32 v48, 16, v48
	v_mul_f32_e32 v38, v36, v41
	v_rcp_f32_e32 v41, v40
	v_mul_f32_e32 v38, v243, v38
	v_mul_f32_e32 v39, v39, v48
	v_cvt_pk_bf16_f32 v38, v38, s0
	v_cvt_pk_bf16_f32 v39, v39, s0
	v_and_b32_e32 v138, 0xffff, v38
	ds_write_b16 v137, v39 offset:2176
	ds_write_b16 v137, v38 offset:19584
	v_mul_f32_e32 v39, v37, v40
	v_mul_f32_e32 v40, v63, v147
	v_lshlrev_b32_e32 v49, 16, v49
	v_mul_f32_e32 v38, v36, v41
	v_rcp_f32_e32 v41, v40
	v_mul_f32_e32 v38, v244, v38
	v_mul_f32_e32 v39, v39, v49
	v_cvt_pk_bf16_f32 v38, v38, s0
	v_cvt_pk_bf16_f32 v39, v39, s0
	v_lshl_or_b32 v140, v38, 16, v138
	ds_write_b16 v137, v39 offset:2448
	ds_write_b16 v137, v38 offset:19856
	v_mul_f32_e32 v39, v37, v40
	v_mul_f32_e32 v40, v61, v147
	v_sub_f32_e32 v245, 1.0, v248
	v_lshlrev_b32_e32 v50, 16, v50
	v_mul_f32_e32 v38, v36, v41
	v_rcp_f32_e32 v41, v40
	v_mul_f32_e32 v38, v245, v38
	v_mul_f32_e32 v39, v39, v50
	v_cvt_pk_bf16_f32 v38, v38, s0
	v_cvt_pk_bf16_f32 v39, v39, s0
	v_and_b32_e32 v138, 0xffff, v38
	ds_write_b16 v137, v39 offset:2720
	ds_write_b16 v137, v38 offset:20128
	v_mul_f32_e32 v39, v37, v40
	v_mul_f32_e32 v40, v60, v147
	v_sub_f32_e32 v246, 1.0, v249
	v_lshlrev_b32_e32 v51, 16, v51
	v_mul_f32_e32 v38, v36, v41
	v_rcp_f32_e32 v41, v40
	v_mul_f32_e32 v38, v246, v38
	v_mul_f32_e32 v39, v39, v51
	v_cvt_pk_bf16_f32 v38, v38, s0
	v_cvt_pk_bf16_f32 v39, v39, s0
	v_lshl_or_b32 v141, v38, 16, v138
	ds_write_b16 v137, v39 offset:2992
	ds_write_b16 v137, v38 offset:20400
	v_mul_f32_e32 v39, v37, v40
	v_mul_f32_e32 v40, v59, v147
	v_lshlrev_b32_e32 v53, 16, v53
	v_mul_f32_e32 v38, v36, v41
	v_rcp_f32_e32 v41, v40
	v_mul_f32_e32 v38, v247, v38
	v_mul_f32_e32 v39, v39, v53
	v_cvt_pk_bf16_f32 v38, v38, s0
	v_cvt_pk_bf16_f32 v39, v39, s0
	v_and_b32_e32 v138, 0xffff, v38
	ds_write_b16 v132, v39 offset:3264
	ds_write_b16 v132, v38 offset:20672
	v_mul_f32_e32 v39, v37, v40
	v_mul_f32_e32 v40, v57, v147
	v_sub_f32_e32 v248, 1.0, v251
	v_lshlrev_b32_e32 v54, 16, v54
	v_mul_f32_e32 v38, v36, v41
	v_rcp_f32_e32 v41, v40
	v_mul_f32_e32 v38, v248, v38
	v_mul_f32_e32 v39, v39, v54
	v_cvt_pk_bf16_f32 v38, v38, s0
	v_cvt_pk_bf16_f32 v39, v39, s0
	v_lshl_or_b32 v142, v38, 16, v138
	ds_write_b16 v132, v39 offset:3536
	ds_write_b16 v132, v38 offset:20944
	v_mul_f32_e32 v39, v37, v40
	v_mul_f32_e32 v40, v56, v147
	v_mul_f32_e32 v38, v36, v41
	v_rcp_f32_e32 v41, v40
	v_sub_f32_e32 v249, 1.0, v252
	v_lshlrev_b32_e32 v55, 16, v55
	v_mul_f32_e32 v38, v249, v38
	v_mul_f32_e32 v39, v39, v55
	v_cvt_pk_bf16_f32 v38, v38, s0
	v_cvt_pk_bf16_f32 v39, v39, s0
	v_sub_f32_e32 v146, 1.0, v146
	v_lshlrev_b32_e32 v52, 16, v52
	v_and_b32_e32 v138, 0xffff, v38
	ds_write_b16 v132, v39 offset:3808
	ds_write_b16 v132, v38 offset:21216
	v_mul_f32_e32 v38, v36, v41
	v_mul_f32_e32 v39, v37, v40
	v_mul_f32_e32 v38, v146, v38
	v_mul_f32_e32 v39, v39, v52
	v_cvt_pk_bf16_f32 v38, v38, s0
	v_cvt_pk_bf16_f32 v39, v39, s0
	v_lshl_or_b32 v143, v38, 16, v138
	ds_write_b128 v136, v[140:143] offset:34832
	ds_write_b16 v132, v39 offset:4080
	ds_write_b16 v132, v38 offset:21488
	s_and_saveexec_b64 s[12:13], s[36:37]
	s_cbranch_execz .LBB0_675
	s_waitcnt lgkmcnt(14)
	v_mul_f32_e32 v34, v34, v35
	v_mul_f32_e32 v34, v36, v34
	v_mul_f32_e32 v35, v37, v34
	ds_write_b32 v95, v36
	ds_write_b32 v94, v35
	ds_write_b32 v93, v34
	s_branch .LBB0_675
